# speedup vs baseline: 1.1070x; 1.0175x over previous
; __device__ __forceinline__ float siluf_(float x) { return x * __builtin_amdgcn_rcpf(1.0f + __builtin_amdgcn_exp2f(-1.4426950408889634f * x)); }
;     ...
;     } else if constexpr (EPI == EPI_SWIGLU) {
;       u16* Gp = (u16*)(ws + OFF_G);
; #pragma unroll
;       for (int m = 0; m < MT; ++m)
; #pragma unroll
;         for (int h = 0; h < 2; ++h) {
;           u32x2 pk;
;           pk.x = pack2(siluf_(acc[m][h][0]) * acc[m][2 + h][0], siluf_(acc[m][h][1]) * acc[m][2 + h][1]);
;           pk.y = pack2(siluf_(acc[m][h][2]) * acc[m][2 + h][2], siluf_(acc[m][h][3]) * acc[m][2 + h][3]);
;           *(u32x2*)(Gp + (size_t)(rbase + m * 16) * DFF + pn * 128 + wc * 32 + h * 16 + fq * 4) = pk;
;         }
.LBB0_182:
	v_mfma_f32_16x16x32_bf16 v[44:47], v[156:159], v[28:31], v[52:55]
	v_mfma_f32_16x16x32_bf16 v[52:55], v[160:163], v[28:31], v[168:171]
	v_mfma_f32_16x16x32_bf16 v[40:43], v[164:167], v[28:31], v[40:43]
	v_mfma_f32_16x16x32_bf16 v[36:39], v[152:155], v[176:179], v[36:39]
	v_mfma_f32_16x16x32_bf16 v[28:31], v[156:159], v[176:179], v[32:35]
	v_mfma_f32_16x16x32_bf16 v[32:35], v[160:163], v[176:179], v[172:175]
	v_mfma_f32_16x16x32_bf16 v[24:27], v[164:167], v[176:179], v[24:27]
	s_lshl_b32 s0, s25, 7
	s_ashr_i32 s1, s0, 31
	v_lshl_add_u32 v154, s50, 8, v223
	v_lshl_add_u64 v[152:153], s[0:1], 1, v[216:217]
	v_mad_i64_i32 v[156:157], s[0:1], v154, s53, v[152:153]
	s_mov_b32 s98, 0x16000
	s_mov_b32 s99, 0
	s_mov_b32 s100, 0xbfb8aa3b
	s_mov_b32 s101, 0xbfb8aa3b
	v_bfe_u32 v154, v228, 4, 1
	v_mul_u32_u24_e32 v154, 24, v154
	v_mov_b32_e32 v155, 0
	v_lshl_add_u64 v[156:157], v[156:157], 0, v[154:155]
	v_mul_f32_e32 v152, 0xbfb8aa3b, v144
	v_mul_f32_e32 v153, 0xbfb8aa3b, v145
	v_mul_f32_e32 v154, 0xbfb8aa3b, v146
	v_mul_f32_e32 v155, 0xbfb8aa3b, v147
	v_exp_f32_e32 v152, v152
	v_exp_f32_e32 v153, v153
	v_exp_f32_e32 v154, v154
	v_exp_f32_e32 v155, v155
	v_add_f32_e32 v152, 1.0, v152
	v_add_f32_e32 v153, 1.0, v153
	v_add_f32_e32 v154, 1.0, v154
	v_add_f32_e32 v155, 1.0, v155
	v_rcp_f32_e32 v152, v152
	v_rcp_f32_e32 v153, v153
	v_rcp_f32_e32 v154, v154
	v_rcp_f32_e32 v155, v155
	v_pk_mul_f32 v[144:145], v[144:145], v[152:153]
	v_pk_mul_f32 v[146:147], v[146:147], v[154:155]
	v_pk_mul_f32 v[144:145], v[144:145], v[148:149]
	v_pk_mul_f32 v[146:147], v[146:147], v[150:151]
	v_cvt_pk_bf16_f32 v144, v144, v145
	v_cvt_pk_bf16_f32 v145, v146, v147
	v_mul_f32_e32 v152, 0xbfb8aa3b, v140
	v_mul_f32_e32 v153, 0xbfb8aa3b, v141
	v_mul_f32_e32 v154, 0xbfb8aa3b, v142
	v_mul_f32_e32 v155, 0xbfb8aa3b, v143
	v_exp_f32_e32 v152, v152
	v_exp_f32_e32 v153, v153
	v_exp_f32_e32 v154, v154
	v_exp_f32_e32 v155, v155
	v_add_f32_e32 v152, 1.0, v152
	v_add_f32_e32 v153, 1.0, v153
	v_add_f32_e32 v154, 1.0, v154
	v_add_f32_e32 v155, 1.0, v155
	v_rcp_f32_e32 v152, v152
	v_rcp_f32_e32 v153, v153
	v_rcp_f32_e32 v154, v154
	v_rcp_f32_e32 v155, v155
	v_pk_mul_f32 v[140:141], v[140:141], v[152:153]
	v_pk_mul_f32 v[142:143], v[142:143], v[154:155]
	v_pk_mul_f32 v[140:141], v[140:141], v[136:137]
	v_pk_mul_f32 v[142:143], v[142:143], v[138:139]
	v_cvt_pk_bf16_f32 v146, v140, v141
	v_cvt_pk_bf16_f32 v147, v142, v143
	s_nop 1
	v_permlane16_swap_b32_e32 v144, v146
	v_permlane16_swap_b32_e32 v145, v147
	global_store_dwordx4 v[156:157], v[144:147], off
	v_lshl_add_u64 v[156:157], v[156:157], 0, s[98:99]
	v_mul_f32_e32 v152, 0xbfb8aa3b, v132
	v_mul_f32_e32 v153, 0xbfb8aa3b, v133
	v_mul_f32_e32 v154, 0xbfb8aa3b, v134
	v_mul_f32_e32 v155, 0xbfb8aa3b, v135
	v_exp_f32_e32 v152, v152
	v_exp_f32_e32 v153, v153
	v_exp_f32_e32 v154, v154
	v_exp_f32_e32 v155, v155
	v_add_f32_e32 v152, 1.0, v152
	v_add_f32_e32 v153, 1.0, v153
	v_add_f32_e32 v154, 1.0, v154
	v_add_f32_e32 v155, 1.0, v155
	v_rcp_f32_e32 v152, v152
	v_rcp_f32_e32 v153, v153
	v_rcp_f32_e32 v154, v154
	v_rcp_f32_e32 v155, v155
	v_pk_mul_f32 v[132:133], v[132:133], v[152:153]
	v_pk_mul_f32 v[134:135], v[134:135], v[154:155]
	v_pk_mul_f32 v[132:133], v[132:133], v[128:129]
	v_pk_mul_f32 v[134:135], v[134:135], v[130:131]
	v_cvt_pk_bf16_f32 v132, v132, v133
	v_cvt_pk_bf16_f32 v133, v134, v135
	v_mul_f32_e32 v152, 0xbfb8aa3b, v124
	v_mul_f32_e32 v153, 0xbfb8aa3b, v125
	v_mul_f32_e32 v154, 0xbfb8aa3b, v126
	v_mul_f32_e32 v155, 0xbfb8aa3b, v127
	v_exp_f32_e32 v152, v152
	v_exp_f32_e32 v153, v153
	v_exp_f32_e32 v154, v154
	v_exp_f32_e32 v155, v155
	v_add_f32_e32 v152, 1.0, v152
	v_add_f32_e32 v153, 1.0, v153
	v_add_f32_e32 v154, 1.0, v154
	v_add_f32_e32 v155, 1.0, v155
	v_rcp_f32_e32 v152, v152
	v_rcp_f32_e32 v153, v153
	v_rcp_f32_e32 v154, v154
	v_rcp_f32_e32 v155, v155
	v_pk_mul_f32 v[124:125], v[124:125], v[152:153]
	v_pk_mul_f32 v[126:127], v[126:127], v[154:155]
	v_pk_mul_f32 v[124:125], v[124:125], v[120:121]
	v_pk_mul_f32 v[126:127], v[126:127], v[122:123]
	v_cvt_pk_bf16_f32 v134, v124, v125
	v_cvt_pk_bf16_f32 v135, v126, v127
	s_nop 1
	v_permlane16_swap_b32_e32 v132, v134
	v_permlane16_swap_b32_e32 v133, v135
	global_store_dwordx4 v[156:157], v[132:135], off
	v_lshl_add_u64 v[156:157], v[156:157], 0, s[98:99]
	v_mul_f32_e32 v152, 0xbfb8aa3b, v112
	v_mul_f32_e32 v153, 0xbfb8aa3b, v113
	v_mul_f32_e32 v154, 0xbfb8aa3b, v114
	v_mul_f32_e32 v155, 0xbfb8aa3b, v115
	v_exp_f32_e32 v152, v152
	v_exp_f32_e32 v153, v153
	v_exp_f32_e32 v154, v154
	v_exp_f32_e32 v155, v155
	v_add_f32_e32 v152, 1.0, v152
	v_add_f32_e32 v153, 1.0, v153
	v_add_f32_e32 v154, 1.0, v154
	v_add_f32_e32 v155, 1.0, v155
	v_rcp_f32_e32 v152, v152
	v_rcp_f32_e32 v153, v153
	v_rcp_f32_e32 v154, v154
	v_rcp_f32_e32 v155, v155
	v_pk_mul_f32 v[112:113], v[112:113], v[152:153]
	v_pk_mul_f32 v[114:115], v[114:115], v[154:155]
	v_pk_mul_f32 v[112:113], v[112:113], v[116:117]
	v_pk_mul_f32 v[114:115], v[114:115], v[118:119]
	v_cvt_pk_bf16_f32 v112, v112, v113
	v_cvt_pk_bf16_f32 v113, v114, v115
	v_mul_f32_e32 v152, 0xbfb8aa3b, v108
	v_mul_f32_e32 v153, 0xbfb8aa3b, v109
	v_mul_f32_e32 v154, 0xbfb8aa3b, v110
	v_mul_f32_e32 v155, 0xbfb8aa3b, v111
	v_exp_f32_e32 v152, v152
	v_exp_f32_e32 v153, v153
	v_exp_f32_e32 v154, v154
	v_exp_f32_e32 v155, v155
	v_add_f32_e32 v152, 1.0, v152
	v_add_f32_e32 v153, 1.0, v153
	v_add_f32_e32 v154, 1.0, v154
	v_add_f32_e32 v155, 1.0, v155
	v_rcp_f32_e32 v152, v152
	v_rcp_f32_e32 v153, v153
	v_rcp_f32_e32 v154, v154
	v_rcp_f32_e32 v155, v155
	v_pk_mul_f32 v[108:109], v[108:109], v[152:153]
	v_pk_mul_f32 v[110:111], v[110:111], v[154:155]
; __device__ __forceinline__ float siluf_(float x) { return x * __builtin_amdgcn_rcpf(1.0f + __builtin_amdgcn_exp2f(-1.4426950408889634f * x)); }
;     ...
;     } else if constexpr (EPI == EPI_SWIGLU) {
;       u16* Gp = (u16*)(ws + OFF_G);
; #pragma unroll
;       for (int m = 0; m < MT; ++m)
; #pragma unroll
;         for (int h = 0; h < 2; ++h) {
;           u32x2 pk;
;           pk.x = pack2(siluf_(acc[m][h][0]) * acc[m][2 + h][0], siluf_(acc[m][h][1]) * acc[m][2 + h][1]);
;           pk.y = pack2(siluf_(acc[m][h][2]) * acc[m][2 + h][2], siluf_(acc[m][h][3]) * acc[m][2 + h][3]);
;           *(u32x2*)(Gp + (size_t)(rbase + m * 16) * DFF + pn * 128 + wc * 32 + h * 16 + fq * 4) = pk;
;         }
	v_pk_mul_f32 v[108:109], v[108:109], v[104:105]
	v_pk_mul_f32 v[110:111], v[110:111], v[106:107]
	v_cvt_pk_bf16_f32 v114, v108, v109
	v_cvt_pk_bf16_f32 v115, v110, v111
	s_nop 1
	v_permlane16_swap_b32_e32 v112, v114
	v_permlane16_swap_b32_e32 v113, v115
	global_store_dwordx4 v[156:157], v[112:115], off
	v_lshl_add_u64 v[156:157], v[156:157], 0, s[98:99]
	v_mul_f32_e32 v152, 0xbfb8aa3b, v100
	v_mul_f32_e32 v153, 0xbfb8aa3b, v101
	v_mul_f32_e32 v154, 0xbfb8aa3b, v102
	v_mul_f32_e32 v155, 0xbfb8aa3b, v103
	v_exp_f32_e32 v152, v152
	v_exp_f32_e32 v153, v153
	v_exp_f32_e32 v154, v154
	v_exp_f32_e32 v155, v155
	v_add_f32_e32 v152, 1.0, v152
	v_add_f32_e32 v153, 1.0, v153
	v_add_f32_e32 v154, 1.0, v154
	v_add_f32_e32 v155, 1.0, v155
	v_rcp_f32_e32 v152, v152
	v_rcp_f32_e32 v153, v153
	v_rcp_f32_e32 v154, v154
	v_rcp_f32_e32 v155, v155
	v_pk_mul_f32 v[100:101], v[100:101], v[152:153]
	v_pk_mul_f32 v[102:103], v[102:103], v[154:155]
	v_pk_mul_f32 v[100:101], v[100:101], v[96:97]
	v_pk_mul_f32 v[102:103], v[102:103], v[98:99]
	v_cvt_pk_bf16_f32 v100, v100, v101
	v_cvt_pk_bf16_f32 v101, v102, v103
	v_mul_f32_e32 v152, 0xbfb8aa3b, v92
	v_mul_f32_e32 v153, 0xbfb8aa3b, v93
	v_mul_f32_e32 v154, 0xbfb8aa3b, v94
	v_mul_f32_e32 v155, 0xbfb8aa3b, v95
	v_exp_f32_e32 v152, v152
	v_exp_f32_e32 v153, v153
	v_exp_f32_e32 v154, v154
	v_exp_f32_e32 v155, v155
	v_add_f32_e32 v152, 1.0, v152
	v_add_f32_e32 v153, 1.0, v153
	v_add_f32_e32 v154, 1.0, v154
	v_add_f32_e32 v155, 1.0, v155
	v_rcp_f32_e32 v152, v152
	v_rcp_f32_e32 v153, v153
	v_rcp_f32_e32 v154, v154
	v_rcp_f32_e32 v155, v155
	v_pk_mul_f32 v[92:93], v[92:93], v[152:153]
	v_pk_mul_f32 v[94:95], v[94:95], v[154:155]
	v_pk_mul_f32 v[92:93], v[92:93], v[88:89]
	v_pk_mul_f32 v[94:95], v[94:95], v[90:91]
	v_cvt_pk_bf16_f32 v102, v92, v93
	v_cvt_pk_bf16_f32 v103, v94, v95
	s_nop 1
	v_permlane16_swap_b32_e32 v100, v102
	v_permlane16_swap_b32_e32 v101, v103
	global_store_dwordx4 v[156:157], v[100:103], off
	v_lshl_add_u64 v[156:157], v[156:157], 0, s[98:99]
	v_mul_f32_e32 v152, 0xbfb8aa3b, v80
	v_mul_f32_e32 v153, 0xbfb8aa3b, v81
	v_mul_f32_e32 v154, 0xbfb8aa3b, v82
	v_mul_f32_e32 v155, 0xbfb8aa3b, v83
	v_exp_f32_e32 v152, v152
	v_exp_f32_e32 v153, v153
	v_exp_f32_e32 v154, v154
	v_exp_f32_e32 v155, v155
	v_add_f32_e32 v152, 1.0, v152
	v_add_f32_e32 v153, 1.0, v153
	v_add_f32_e32 v154, 1.0, v154
	v_add_f32_e32 v155, 1.0, v155
	v_rcp_f32_e32 v152, v152
	v_rcp_f32_e32 v153, v153
	v_rcp_f32_e32 v154, v154
	v_rcp_f32_e32 v155, v155
	v_pk_mul_f32 v[80:81], v[80:81], v[152:153]
	v_pk_mul_f32 v[82:83], v[82:83], v[154:155]
	v_pk_mul_f32 v[80:81], v[80:81], v[84:85]
	v_pk_mul_f32 v[82:83], v[82:83], v[86:87]
	v_cvt_pk_bf16_f32 v80, v80, v81
	v_cvt_pk_bf16_f32 v81, v82, v83
	v_mul_f32_e32 v152, 0xbfb8aa3b, v76
	v_mul_f32_e32 v153, 0xbfb8aa3b, v77
	v_mul_f32_e32 v154, 0xbfb8aa3b, v78
	v_mul_f32_e32 v155, 0xbfb8aa3b, v79
	v_exp_f32_e32 v152, v152
	v_exp_f32_e32 v153, v153
	v_exp_f32_e32 v154, v154
	v_exp_f32_e32 v155, v155
	v_add_f32_e32 v152, 1.0, v152
	v_add_f32_e32 v153, 1.0, v153
	v_add_f32_e32 v154, 1.0, v154
	v_add_f32_e32 v155, 1.0, v155
	v_rcp_f32_e32 v152, v152
	v_rcp_f32_e32 v153, v153
	v_rcp_f32_e32 v154, v154
	v_rcp_f32_e32 v155, v155
	v_pk_mul_f32 v[76:77], v[76:77], v[152:153]
	v_pk_mul_f32 v[78:79], v[78:79], v[154:155]
	v_pk_mul_f32 v[76:77], v[76:77], v[72:73]
	v_pk_mul_f32 v[78:79], v[78:79], v[74:75]
	v_cvt_pk_bf16_f32 v82, v76, v77
	v_cvt_pk_bf16_f32 v83, v78, v79
	s_nop 1
	v_permlane16_swap_b32_e32 v80, v82
	v_permlane16_swap_b32_e32 v81, v83
	global_store_dwordx4 v[156:157], v[80:83], off
	v_lshl_add_u64 v[156:157], v[156:157], 0, s[98:99]
	v_mul_f32_e32 v152, 0xbfb8aa3b, v68
	v_mul_f32_e32 v153, 0xbfb8aa3b, v69
	v_mul_f32_e32 v154, 0xbfb8aa3b, v70
	v_mul_f32_e32 v155, 0xbfb8aa3b, v71
	v_exp_f32_e32 v152, v152
	v_exp_f32_e32 v153, v153
	v_exp_f32_e32 v154, v154
	v_exp_f32_e32 v155, v155
	v_add_f32_e32 v152, 1.0, v152
	v_add_f32_e32 v153, 1.0, v153
	v_add_f32_e32 v154, 1.0, v154
	v_add_f32_e32 v155, 1.0, v155
	v_rcp_f32_e32 v152, v152
	v_rcp_f32_e32 v153, v153
	v_rcp_f32_e32 v154, v154
	v_rcp_f32_e32 v155, v155
	v_pk_mul_f32 v[68:69], v[68:69], v[152:153]
	v_pk_mul_f32 v[70:71], v[70:71], v[154:155]
	v_pk_mul_f32 v[68:69], v[68:69], v[64:65]
	v_pk_mul_f32 v[70:71], v[70:71], v[66:67]
; __device__ __forceinline__ float siluf_(float x) { return x * __builtin_amdgcn_rcpf(1.0f + __builtin_amdgcn_exp2f(-1.4426950408889634f * x)); }
;     ...
;     } else if constexpr (EPI == EPI_SWIGLU) {
;       u16* Gp = (u16*)(ws + OFF_G);
; #pragma unroll
;       for (int m = 0; m < MT; ++m)
; #pragma unroll
;         for (int h = 0; h < 2; ++h) {
;           u32x2 pk;
;           pk.x = pack2(siluf_(acc[m][h][0]) * acc[m][2 + h][0], siluf_(acc[m][h][1]) * acc[m][2 + h][1]);
;           pk.y = pack2(siluf_(acc[m][h][2]) * acc[m][2 + h][2], siluf_(acc[m][h][3]) * acc[m][2 + h][3]);
;           *(u32x2*)(Gp + (size_t)(rbase + m * 16) * DFF + pn * 128 + wc * 32 + h * 16 + fq * 4) = pk;
;         }
	v_cvt_pk_bf16_f32 v68, v68, v69
	v_cvt_pk_bf16_f32 v69, v70, v71
	v_mul_f32_e32 v152, 0xbfb8aa3b, v60
	v_mul_f32_e32 v153, 0xbfb8aa3b, v61
	v_mul_f32_e32 v154, 0xbfb8aa3b, v62
	v_mul_f32_e32 v155, 0xbfb8aa3b, v63
	v_exp_f32_e32 v152, v152
	v_exp_f32_e32 v153, v153
	v_exp_f32_e32 v154, v154
	v_exp_f32_e32 v155, v155
	v_add_f32_e32 v152, 1.0, v152
	v_add_f32_e32 v153, 1.0, v153
	v_add_f32_e32 v154, 1.0, v154
	v_add_f32_e32 v155, 1.0, v155
	v_rcp_f32_e32 v152, v152
	v_rcp_f32_e32 v153, v153
	v_rcp_f32_e32 v154, v154
	v_rcp_f32_e32 v155, v155
	v_pk_mul_f32 v[60:61], v[60:61], v[152:153]
	v_pk_mul_f32 v[62:63], v[62:63], v[154:155]
	v_pk_mul_f32 v[60:61], v[60:61], v[56:57]
	v_pk_mul_f32 v[62:63], v[62:63], v[58:59]
	v_cvt_pk_bf16_f32 v70, v60, v61
	v_cvt_pk_bf16_f32 v71, v62, v63
	s_nop 1
	v_permlane16_swap_b32_e32 v68, v70
	v_permlane16_swap_b32_e32 v69, v71
	global_store_dwordx4 v[156:157], v[68:71], off
	v_lshl_add_u64 v[156:157], v[156:157], 0, s[98:99]
	v_mul_f32_e32 v152, 0xbfb8aa3b, v48
	v_mul_f32_e32 v153, 0xbfb8aa3b, v49
	v_mul_f32_e32 v154, 0xbfb8aa3b, v50
	v_mul_f32_e32 v155, 0xbfb8aa3b, v51
	v_exp_f32_e32 v152, v152
	v_exp_f32_e32 v153, v153
	v_exp_f32_e32 v154, v154
	v_exp_f32_e32 v155, v155
	v_add_f32_e32 v152, 1.0, v152
	v_add_f32_e32 v153, 1.0, v153
	v_add_f32_e32 v154, 1.0, v154
	v_add_f32_e32 v155, 1.0, v155
	v_rcp_f32_e32 v152, v152
	v_rcp_f32_e32 v153, v153
	v_rcp_f32_e32 v154, v154
	v_rcp_f32_e32 v155, v155
	v_pk_mul_f32 v[48:49], v[48:49], v[152:153]
	v_pk_mul_f32 v[50:51], v[50:51], v[154:155]
	v_pk_mul_f32 v[48:49], v[48:49], v[52:53]
	v_pk_mul_f32 v[50:51], v[50:51], v[54:55]
	v_cvt_pk_bf16_f32 v48, v48, v49
	v_cvt_pk_bf16_f32 v49, v50, v51
	v_mul_f32_e32 v152, 0xbfb8aa3b, v44
	v_mul_f32_e32 v153, 0xbfb8aa3b, v45
	v_mul_f32_e32 v154, 0xbfb8aa3b, v46
	v_mul_f32_e32 v155, 0xbfb8aa3b, v47
	v_exp_f32_e32 v152, v152
	v_exp_f32_e32 v153, v153
	v_exp_f32_e32 v154, v154
	v_exp_f32_e32 v155, v155
	v_add_f32_e32 v152, 1.0, v152
	v_add_f32_e32 v153, 1.0, v153
	v_add_f32_e32 v154, 1.0, v154
	v_add_f32_e32 v155, 1.0, v155
	v_rcp_f32_e32 v152, v152
	v_rcp_f32_e32 v153, v153
	v_rcp_f32_e32 v154, v154
	v_rcp_f32_e32 v155, v155
	v_pk_mul_f32 v[44:45], v[44:45], v[152:153]
	v_pk_mul_f32 v[46:47], v[46:47], v[154:155]
	v_pk_mul_f32 v[44:45], v[44:45], v[40:41]
	v_pk_mul_f32 v[46:47], v[46:47], v[42:43]
	v_cvt_pk_bf16_f32 v50, v44, v45
	v_cvt_pk_bf16_f32 v51, v46, v47
	s_nop 1
	v_permlane16_swap_b32_e32 v48, v50
	v_permlane16_swap_b32_e32 v49, v51
	global_store_dwordx4 v[156:157], v[48:51], off
	v_lshl_add_u64 v[156:157], v[156:157], 0, s[98:99]
	v_mul_f32_e32 v152, 0xbfb8aa3b, v36
	v_mul_f32_e32 v153, 0xbfb8aa3b, v37
	v_mul_f32_e32 v154, 0xbfb8aa3b, v38
	v_mul_f32_e32 v155, 0xbfb8aa3b, v39
	v_exp_f32_e32 v152, v152
	v_exp_f32_e32 v153, v153
	v_exp_f32_e32 v154, v154
	v_exp_f32_e32 v155, v155
	v_add_f32_e32 v152, 1.0, v152
	v_add_f32_e32 v153, 1.0, v153
	v_add_f32_e32 v154, 1.0, v154
	v_add_f32_e32 v155, 1.0, v155
	v_rcp_f32_e32 v152, v152
	v_rcp_f32_e32 v153, v153
	v_rcp_f32_e32 v154, v154
	v_rcp_f32_e32 v155, v155
	v_pk_mul_f32 v[36:37], v[36:37], v[152:153]
	v_pk_mul_f32 v[38:39], v[38:39], v[154:155]
	v_pk_mul_f32 v[36:37], v[36:37], v[32:33]
	v_pk_mul_f32 v[38:39], v[38:39], v[34:35]
	v_cvt_pk_bf16_f32 v36, v36, v37
	v_cvt_pk_bf16_f32 v37, v38, v39
	v_mul_f32_e32 v152, 0xbfb8aa3b, v28
	v_mul_f32_e32 v153, 0xbfb8aa3b, v29
	v_mul_f32_e32 v154, 0xbfb8aa3b, v30
	v_mul_f32_e32 v155, 0xbfb8aa3b, v31
	v_exp_f32_e32 v152, v152
	v_exp_f32_e32 v153, v153
	v_exp_f32_e32 v154, v154
	v_exp_f32_e32 v155, v155
	v_add_f32_e32 v152, 1.0, v152
	v_add_f32_e32 v153, 1.0, v153
	v_add_f32_e32 v154, 1.0, v154
	v_add_f32_e32 v155, 1.0, v155
	v_rcp_f32_e32 v152, v152
	v_rcp_f32_e32 v153, v153
	v_rcp_f32_e32 v154, v154
	v_rcp_f32_e32 v155, v155
	v_pk_mul_f32 v[28:29], v[28:29], v[152:153]
	v_pk_mul_f32 v[30:31], v[30:31], v[154:155]
	v_pk_mul_f32 v[28:29], v[28:29], v[24:25]
	v_pk_mul_f32 v[30:31], v[30:31], v[26:27]
	v_cvt_pk_bf16_f32 v38, v28, v29
	v_cvt_pk_bf16_f32 v39, v30, v31
	s_nop 1
	v_permlane16_swap_b32_e32 v36, v38
	v_permlane16_swap_b32_e32 v37, v39
	global_store_dwordx4 v[156:157], v[36:39], off
	s_and_b64 vcc, exec, s[12:13]
	s_mov_b32 s50, s23
	s_mov_b32 s25, s21
	s_mov_b64 s[16:17], s[6:7]
	s_mov_b64 s[0:1], s[10:11]
	s_cbranch_vccnz .LBB0_191
